# GEMM prologue address math and first weight-tile LDS-DMA loads issued before the grid sync's closing barrier (waves 1-7 prefetch B during the barrier protocol) for out/up/down projections
# speedup vs baseline: 1.0336x; 1.0021x over previous
.LBB0_697:
	s_or_b64 exec, exec, s[36:37]
	v_readlane_b32 s0, v252, 2
	v_readlane_b32 s1, v252, 3
	s_add_u32 s28, s72, 0x600000
	s_addc_u32 s29, s8, 0
	v_cndmask_b32_e64 v0, 0, 1, s[0:1]
	v_cmp_ne_u32_e64 s[4:5], 1, v0
	s_add_u32 s76, s96, 0x10800
	s_addc_u32 s77, s97, 0
	v_mov_b32_e32 v10, v226
	v_writelane_b32 v252, s4, 50
	v_writelane_b32 v252, s5, 51
	s_andn2_b64 vcc, exec, s[0:1]
	v_readfirstlane_b32 s4, v10
	s_cbranch_vccnz .Lbpf_skip_out
	v_lshlrev_b32_e32 v0, 4, v10
	v_add_u32_e32 v1, 0x2000, v0
	v_ashrrev_i32_e32 v2, 31, v1
	v_lshrrev_b32_e32 v2, 22, v2
	v_add_u32_e32 v2, v1, v2
	v_ashrrev_i32_e32 v4, 10, v2
	v_mul_i32_i24_e32 v2, 0x400, v4
	v_sub_u32_e32 v1, v1, v2
	v_lshrrev_b32_e32 v2, 4, v1
	v_bitop3_b32 v1, v2, v1, 32 bitop3:0x6c
	v_ashrrev_i32_e32 v2, 31, v1
	v_lshrrev_b32_e32 v2, 26, v2
	v_add_u32_e32 v2, v1, v2
	v_lshlrev_b32_e32 v3, 3, v4
	v_ashrrev_i32_e32 v5, 6, v2
	v_and_b32_e32 v3, -16, v3
	v_add_u32_e32 v3, v5, v3
	v_and_b32_e32 v6, 3, v5
	s_mov_b32 s0, 0x1fffe0
	v_lshrrev_b32_e32 v7, 2, v3
	v_lshlrev_b32_e32 v8, 1, v3
	v_and_b32_e32 v2, 0xc0, v2
	v_and_or_b32 v6, v3, s0, v6
	v_and_b32_e32 v7, 4, v7
	v_and_b32_e32 v8, 24, v8
	v_sub_u32_e32 v1, v1, v2
	v_or3_b32 v7, v6, v7, v8
	v_lshlrev_b32_e32 v6, 5, v4
	v_ashrrev_i16_sdwa v1, v229, sext(v1) dst_sel:DWORD dst_unused:UNUSED_PAD src0_sel:DWORD src1_sel:BYTE_0
	v_and_b32_e32 v8, 32, v6
	v_bfe_i32 v6, v1, 0, 16
	v_add_lshl_u32 v1, v8, v6, 1
	v_lshl_add_u32 v128, v7, 11, v1
	v_lshl_add_u32 v130, v3, 11, v1
	v_bfe_i32 v1, v10, 27, 1
	v_lshrrev_b32_e32 v1, 22, v1
	v_add_u32_e32 v1, v0, v1
	v_and_b32_e32 v1, 0xfffffc00, v1
	v_sub_u32_e32 v0, v0, v1
	v_lshrrev_b32_e32 v1, 4, v0
	v_ashrrev_i32_e32 v2, 31, v10
	v_bitop3_b32 v0, v1, v0, 32 bitop3:0x6c
	v_lshrrev_b32_e32 v2, 26, v2
	v_ashrrev_i32_e32 v1, 31, v0
	v_add_u32_e32 v2, v10, v2
	v_lshrrev_b32_e32 v1, 26, v1
	v_ashrrev_i32_e32 v8, 6, v2
	v_add_u32_e32 v1, v0, v1
	v_lshlrev_b32_e32 v2, 3, v8
	v_ashrrev_i32_e32 v7, 6, v1
	v_and_b32_e32 v2, -16, v2
	v_add_u32_e32 v2, v7, v2
	v_and_b32_e32 v3, 3, v7
	v_lshrrev_b32_e32 v9, 2, v2
	v_lshlrev_b32_e32 v11, 1, v2
	v_and_b32_e32 v1, 0xc0, v1
	s_ashr_i32 s5, s4, 6
	v_and_or_b32 v3, v2, s0, v3
	v_and_b32_e32 v9, 4, v9
	v_and_b32_e32 v11, 24, v11
	v_sub_u32_e32 v0, v0, v1
	s_ashr_i32 s6, s4, 8
	s_lshl_b32 s30, s5, 10
	v_or3_b32 v3, v3, v9, v11
	v_lshlrev_b32_e32 v9, 5, v8
	v_ashrrev_i16_sdwa v0, v229, sext(v0) dst_sel:DWORD dst_unused:UNUSED_PAD src0_sel:DWORD src1_sel:BYTE_0
	v_readlane_b32 s0, v252, 25
	v_and_b32_e32 v11, 32, v9
	v_bfe_i32 v9, v0, 0, 16
	v_readlane_b32 s1, v252, 26
	s_add_u32 s24, s28, s0
	v_add_lshl_u32 v0, v11, v9, 1
	s_addc_u32 s25, s29, s1
	s_add_i32 s31, s30, 0
	v_lshl_add_u32 v208, v3, 11, v0
	s_add_i32 m0, s31, 0x10000
	v_lshl_add_u32 v132, v2, 11, v0
	global_load_lds_dwordx4 v208, s[24:25]
	s_add_i32 m0, s31, 0x12000
	s_add_u32 s0, s24, 0x40000
	global_load_lds_dwordx4 v128, s[24:25]
	s_addc_u32 s1, s25, 0
	s_add_i32 m0, s31, 0x14000
	s_add_i32 s34, s31, 0x2000
	global_load_lds_dwordx4 v208, s[0:1]
	s_add_i32 m0, s31, 0x16000
	s_add_i32 s35, s31, 0x4000
	global_load_lds_dwordx4 v128, s[0:1]
.Lbpf_skip_out:
	s_waitcnt lgkmcnt(0)
	s_barrier
	s_cbranch_vccnz .LBB0_733
	v_readlane_b32 s0, v252, 27
	s_mov_b32 m0, s31
	v_readlane_b32 s1, v252, 28
	s_add_i32 s36, s31, 0x6000
	v_mov_b32_e32 v129, v209
	s_cmp_eq_u32 s6, 1
	v_lshl_add_u64 v[0:1], s[24:25], 0, v[208:209]
	v_lshl_add_u64 v[2:3], s[24:25], 0, v[128:129]
	global_load_lds_dwordx4 v132, s[0:1]
	s_mov_b32 m0, s34
	s_nop 0
	global_load_lds_dwordx4 v130, s[0:1]
	v_readlane_b32 s0, v252, 29
	s_mov_b32 m0, s35
	v_readlane_b32 s1, v252, 30
	s_nop 4
	global_load_lds_dwordx4 v132, s[0:1]
	s_mov_b32 m0, s36
	s_nop 0
	global_load_lds_dwordx4 v130, s[0:1]
	s_cselect_b64 s[0:1], -1, 0
	s_cmp_lg_u32 s6, 1
	s_cbranch_scc1 .LBB0_700
	s_barrier

.LBB0_782:
	s_or_b64 exec, exec, s[40:41]
	v_readlane_b32 s0, v252, 4
	s_add_u32 s26, s72, 0x800000
	s_addc_u32 s27, s8, 0
	v_mov_b32_e32 v6, v226
	v_readlane_b32 s1, v252, 5
	s_and_b64 vcc, exec, s[0:1]
	v_readfirstlane_b32 s4, v6
	s_cbranch_vccz .Lbpf_skip_up
	v_lshlrev_b32_e32 v3, 4, v6
	v_add_u32_e32 v1, 0x2000, v3
	v_ashrrev_i32_e32 v0, 31, v1
	v_lshrrev_b32_e32 v0, 22, v0
	v_add_u32_e32 v0, v1, v0
	v_ashrrev_i32_e32 v0, 10, v0
	v_mul_i32_i24_e32 v2, 0x400, v0
	v_sub_u32_e32 v1, v1, v2
	v_lshrrev_b32_e32 v2, 4, v1
	v_bitop3_b32 v2, v2, v1, 32 bitop3:0x6c
	v_ashrrev_i32_e32 v1, 31, v2
	v_lshrrev_b32_e32 v1, 26, v1
	v_add_u32_e32 v4, v2, v1
	v_lshlrev_b32_e32 v5, 3, v0
	v_ashrrev_i32_e32 v1, 6, v4
	v_and_b32_e32 v5, -16, v5
	v_add_u32_e32 v5, v1, v5
	v_and_b32_e32 v7, 3, v1
	s_mov_b32 s0, 0x1fffe0
	v_lshrrev_b32_e32 v8, 2, v5
	v_lshlrev_b32_e32 v9, 1, v5
	v_and_b32_e32 v4, 0xc0, v4
	v_and_or_b32 v7, v5, s0, v7
	v_and_b32_e32 v8, 4, v8
	v_and_b32_e32 v9, 24, v9
	v_sub_u32_e32 v2, v2, v4
	v_or3_b32 v7, v7, v8, v9
	v_lshlrev_b32_e32 v8, 5, v0
	v_ashrrev_i16_sdwa v2, v229, sext(v2) dst_sel:DWORD dst_unused:UNUSED_PAD src0_sel:DWORD src1_sel:BYTE_0
	v_and_b32_e32 v8, 32, v8
	v_bfe_i32 v2, v2, 0, 16
	v_add_lshl_u32 v4, v8, v2, 1
	v_lshl_add_u32 v128, v7, 11, v4
	v_lshl_add_u32 v130, v5, 11, v4
	v_bfe_i32 v4, v6, 27, 1
	v_lshrrev_b32_e32 v4, 22, v4
	v_add_u32_e32 v4, v3, v4
	v_and_b32_e32 v4, 0xfffffc00, v4
	v_sub_u32_e32 v3, v3, v4
	v_lshrrev_b32_e32 v4, 4, v3
	v_bitop3_b32 v5, v4, v3, 32 bitop3:0x6c
	v_ashrrev_i32_e32 v4, 31, v6
	v_lshrrev_b32_e32 v4, 26, v4
	v_ashrrev_i32_e32 v3, 31, v5
	v_add_u32_e32 v4, v6, v4
	v_lshrrev_b32_e32 v3, 26, v3
	v_ashrrev_i32_e32 v4, 6, v4
	v_add_u32_e32 v7, v5, v3
	v_lshlrev_b32_e32 v8, 3, v4
	v_ashrrev_i32_e32 v3, 6, v7
	v_and_b32_e32 v8, -16, v8
	v_add_u32_e32 v8, v3, v8
	v_and_b32_e32 v9, 3, v3
	v_lshrrev_b32_e32 v10, 2, v8
	v_lshlrev_b32_e32 v11, 1, v8
	v_and_b32_e32 v7, 0xc0, v7
	s_ashr_i32 s5, s4, 6
	v_and_or_b32 v9, v8, s0, v9
	v_and_b32_e32 v10, 4, v10
	v_and_b32_e32 v11, 24, v11
	v_sub_u32_e32 v5, v5, v7
	s_ashr_i32 s6, s4, 8
	s_lshl_b32 s28, s5, 10
	v_or3_b32 v9, v9, v10, v11
	v_lshlrev_b32_e32 v10, 5, v4
	v_ashrrev_i16_sdwa v5, v229, sext(v5) dst_sel:DWORD dst_unused:UNUSED_PAD src0_sel:DWORD src1_sel:BYTE_0
	v_readlane_b32 s0, v252, 11
	v_and_b32_e32 v10, 32, v10
	v_bfe_i32 v5, v5, 0, 16
	v_readlane_b32 s1, v252, 12
	s_add_u32 s22, s26, s0
	v_add_lshl_u32 v7, v10, v5, 1
	s_addc_u32 s23, s27, s1
	s_add_i32 s29, s28, 0
	v_lshl_add_u32 v208, v9, 11, v7
	s_add_i32 m0, s29, 0x10000
	v_lshl_add_u32 v132, v8, 11, v7
	global_load_lds_dwordx4 v208, s[22:23]
	s_add_i32 m0, s29, 0x12000
	s_add_u32 s0, s22, 0x40000
	global_load_lds_dwordx4 v128, s[22:23]
	s_addc_u32 s1, s23, 0
	s_add_i32 m0, s29, 0x14000
	s_add_i32 s30, s29, 0x2000
	global_load_lds_dwordx4 v208, s[0:1]
	s_add_i32 m0, s29, 0x16000
	s_add_i32 s31, s29, 0x4000
	global_load_lds_dwordx4 v128, s[0:1]
.Lbpf_skip_up:
	s_waitcnt lgkmcnt(0)
	s_barrier
	s_cbranch_vccz .LBB0_802
	v_readlane_b32 s0, v252, 13
	s_mov_b32 m0, s29
	v_readlane_b32 s1, v252, 14
	s_add_i32 s34, s29, 0x6000
	s_cmp_eq_u32 s6, 1
	s_nop 2
	global_load_lds_dwordx4 v132, s[0:1]
	s_mov_b32 m0, s30
	s_nop 0
	global_load_lds_dwordx4 v130, s[0:1]
	v_readlane_b32 s0, v252, 15
	s_mov_b32 m0, s31
	v_readlane_b32 s1, v252, 16
	s_nop 4
	global_load_lds_dwordx4 v132, s[0:1]
	s_mov_b32 m0, s34
	s_nop 0
	global_load_lds_dwordx4 v130, s[0:1]
	s_cselect_b64 s[0:1], -1, 0
	s_cmp_lg_u32 s6, 1
	s_cbranch_scc1 .LBB0_785
	s_barrier

.LBB0_856:
	s_or_b64 exec, exec, s[40:41]
	s_add_u32 s30, s72, 0x1000000
	s_addc_u32 s8, s8, 0
	v_readlane_b32 s0, v252, 50
	s_add_u32 s12, s96, 0x21000
	s_addc_u32 s13, s97, 0
	v_mov_b32_e32 v6, v226
	v_readlane_b32 s1, v252, 51
	s_and_b64 vcc, exec, s[0:1]
	v_readfirstlane_b32 s4, v6
	s_mov_b32 s28, 0x30000
	s_mov_b32 s29, 0x40000
	s_mov_b32 s72, 0x50000
	s_cbranch_vccnz .Lbpf_skip_dn
	v_lshlrev_b32_e32 v3, 4, v6
	v_add_u32_e32 v1, 0x2000, v3
	v_ashrrev_i32_e32 v0, 31, v1
	v_lshrrev_b32_e32 v0, 22, v0
	v_add_u32_e32 v0, v1, v0
	v_ashrrev_i32_e32 v0, 10, v0
	v_mul_i32_i24_e32 v2, 0x400, v0
	v_sub_u32_e32 v1, v1, v2
	v_lshrrev_b32_e32 v2, 4, v1
	v_bitop3_b32 v2, v2, v1, 32 bitop3:0x6c
	v_ashrrev_i32_e32 v1, 31, v2
	v_lshrrev_b32_e32 v1, 26, v1
	v_add_u32_e32 v4, v2, v1
	v_lshlrev_b32_e32 v5, 3, v0
	v_ashrrev_i32_e32 v1, 6, v4
	v_and_b32_e32 v5, -16, v5
	v_add_u32_e32 v5, v1, v5
	v_and_b32_e32 v7, 3, v1
	s_mov_b32 s0, 0x7ffe0
	v_lshrrev_b32_e32 v8, 2, v5
	v_lshlrev_b32_e32 v9, 1, v5
	v_and_b32_e32 v4, 0xc0, v4
	v_and_or_b32 v7, v5, s0, v7
	v_and_b32_e32 v8, 4, v8
	v_and_b32_e32 v9, 24, v9
	v_sub_u32_e32 v2, v2, v4
	v_or3_b32 v7, v7, v8, v9
	v_lshlrev_b32_e32 v8, 5, v0
	v_ashrrev_i16_sdwa v2, v229, sext(v2) dst_sel:DWORD dst_unused:UNUSED_PAD src0_sel:DWORD src1_sel:BYTE_0
	v_and_b32_e32 v8, 32, v8
	v_bfe_i32 v2, v2, 0, 16
	v_add_lshl_u32 v4, v8, v2, 1
	v_lshl_add_u32 v128, v7, 13, v4
	v_lshl_add_u32 v130, v5, 13, v4
	v_bfe_i32 v4, v6, 27, 1
	v_lshrrev_b32_e32 v4, 22, v4
	v_add_u32_e32 v4, v3, v4
	v_and_b32_e32 v4, 0xfffffc00, v4
	v_sub_u32_e32 v3, v3, v4
	v_lshrrev_b32_e32 v4, 4, v3
	v_bitop3_b32 v5, v4, v3, 32 bitop3:0x6c
	v_ashrrev_i32_e32 v4, 31, v6
	v_lshrrev_b32_e32 v4, 26, v4
	v_ashrrev_i32_e32 v3, 31, v5
	v_add_u32_e32 v4, v6, v4
	v_lshrrev_b32_e32 v3, 26, v3
	v_ashrrev_i32_e32 v4, 6, v4
	v_add_u32_e32 v7, v5, v3
	v_lshlrev_b32_e32 v8, 3, v4
	v_ashrrev_i32_e32 v3, 6, v7
	v_and_b32_e32 v8, -16, v8
	v_add_u32_e32 v8, v3, v8
	v_and_b32_e32 v9, 3, v3
	v_lshrrev_b32_e32 v10, 2, v8
	v_lshlrev_b32_e32 v11, 1, v8
	v_and_b32_e32 v7, 0xc0, v7
	s_ashr_i32 s5, s4, 6
	v_and_or_b32 v9, v8, s0, v9
	v_and_b32_e32 v10, 4, v10
	v_and_b32_e32 v11, 24, v11
	v_sub_u32_e32 v5, v5, v7
	s_ashr_i32 s6, s4, 8
	s_lshl_b32 s31, s5, 10
	v_or3_b32 v9, v9, v10, v11
	v_lshlrev_b32_e32 v10, 5, v4
	v_ashrrev_i16_sdwa v5, v229, sext(v5) dst_sel:DWORD dst_unused:UNUSED_PAD src0_sel:DWORD src1_sel:BYTE_0
	v_readlane_b32 s0, v252, 33
	v_and_b32_e32 v10, 32, v10
	v_bfe_i32 v5, v5, 0, 16
	v_readlane_b32 s1, v252, 34
	s_add_u32 s26, s30, s0
	v_add_lshl_u32 v7, v10, v5, 1
	s_addc_u32 s27, s8, s1
	s_add_i32 s34, s31, 0
	v_lshl_add_u32 v208, v9, 13, v7
	s_add_i32 m0, s34, 0x10000
	v_lshl_add_u32 v132, v8, 13, v7
	global_load_lds_dwordx4 v208, s[26:27]
	s_add_i32 m0, s34, 0x12000
	s_add_u32 s0, s26, 0x100000
	global_load_lds_dwordx4 v128, s[26:27]
	s_addc_u32 s1, s27, 0
	s_add_i32 m0, s34, 0x14000
	s_add_i32 s35, s34, 0x2000
	global_load_lds_dwordx4 v208, s[0:1]
	s_add_i32 m0, s34, 0x16000
	s_add_i32 s36, s34, 0x4000
	global_load_lds_dwordx4 v128, s[0:1]
.Lbpf_skip_dn:
	s_waitcnt lgkmcnt(0)
	s_barrier
	s_cbranch_vccnz .LBB0_892
	v_readlane_b32 s0, v252, 35
	s_mov_b32 m0, s34
	v_readlane_b32 s1, v252, 36
	s_add_i32 s37, s34, 0x6000
	s_cmp_eq_u32 s6, 1
	s_nop 2
	global_load_lds_dwordx4 v132, s[0:1]
	s_mov_b32 m0, s35
	s_nop 0
	global_load_lds_dwordx4 v130, s[0:1]
	v_readlane_b32 s0, v252, 37
	s_mov_b32 m0, s36
	v_readlane_b32 s1, v252, 38
	s_nop 4
	global_load_lds_dwordx4 v132, s[0:1]
	s_mov_b32 m0, s37
	s_nop 0
	global_load_lds_dwordx4 v130, s[0:1]
	s_cselect_b64 s[0:1], -1, 0
	s_cmp_lg_u32 s6, 1
	s_cbranch_scc1 .LBB0_859
	s_barrier
